# v50 + unreachable s_nop padding after the rare rescale blocks so later hot loops keep the same 64-byte code alignment as v43
# speedup vs baseline: 1.0016x; 1.0016x over previous
.LBB0_936:
	v_sub_f32_e32 v241, v164, v184
	v_max_f32_e32 v241, v160, v241
	v_sub_f32_e32 v163, v160, v241
	v_exp_f32_e32 v163, v163
	v_add_f32_e32 v242, v241, v184
	v_mov_b32_e32 v160, v241
	v_sub_f32_e32 v84, v84, v242
	v_sub_f32_e32 v85, v85, v242
	v_sub_f32_e32 v86, v86, v242
	v_sub_f32_e32 v87, v87, v242
	v_sub_f32_e32 v88, v88, v242
	v_sub_f32_e32 v89, v89, v242
	v_sub_f32_e32 v90, v90, v242
	v_sub_f32_e32 v91, v91, v242
	v_sub_f32_e32 v92, v92, v242
	v_sub_f32_e32 v93, v93, v242
	v_sub_f32_e32 v94, v94, v242
	v_sub_f32_e32 v95, v95, v242
	v_sub_f32_e32 v96, v96, v242
	v_sub_f32_e32 v97, v97, v242
	v_sub_f32_e32 v98, v98, v242
	v_sub_f32_e32 v99, v99, v242
	v_sub_f32_e32 v68, v68, v242
	v_sub_f32_e32 v69, v69, v242
	v_sub_f32_e32 v70, v70, v242
	v_sub_f32_e32 v71, v71, v242
	v_sub_f32_e32 v72, v72, v242
	v_sub_f32_e32 v73, v73, v242
	v_sub_f32_e32 v74, v74, v242
	v_sub_f32_e32 v75, v75, v242
	v_sub_f32_e32 v76, v76, v242
	v_sub_f32_e32 v77, v77, v242
	v_sub_f32_e32 v78, v78, v242
	v_sub_f32_e32 v79, v79, v242
	v_sub_f32_e32 v80, v80, v242
	v_sub_f32_e32 v81, v81, v242
	v_sub_f32_e32 v82, v82, v242
	v_sub_f32_e32 v83, v83, v242
	v_cmp_lt_f32_e32 vcc, 0xf0000000, v241
	v_sub_f32_e32 v242, 0, v241
	s_nop 0
	v_cndmask_b32_e32 v242, 0, v242, vcc
	v_add_f32_e32 v240, v241, v242
	v_mov_b32_e32 v184, v242
	v_mov_b32_e32 v185, v242
	v_mov_b32_e32 v186, v242
	v_mov_b32_e32 v187, v242
	v_mov_b32_e32 v188, v242
	v_mov_b32_e32 v189, v242
	v_mov_b32_e32 v190, v242
	v_mov_b32_e32 v191, v242
	v_mov_b32_e32 v192, v242
	v_mov_b32_e32 v193, v242
	v_mov_b32_e32 v194, v242
	v_mov_b32_e32 v195, v242
	v_mov_b32_e32 v196, v242
	v_mov_b32_e32 v197, v242
	v_mov_b32_e32 v198, v242
	v_mov_b32_e32 v199, v242
	s_branch .LBB0_932
	s_nop 0
	s_nop 0
	s_nop 0
	s_nop 0
	s_nop 0
	s_nop 0
	s_nop 0
	s_nop 0
	s_nop 0
	s_nop 0
	s_nop 0
	s_nop 0
	s_nop 0
	s_nop 0

.LBB0_962:
	v_sub_f32_e32 v241, v166, v184
	v_max_f32_e32 v241, v162, v241
	v_sub_f32_e32 v165, v162, v241
	v_exp_f32_e32 v165, v165
	v_add_f32_e32 v242, v241, v184
	v_mov_b32_e32 v162, v241
	v_sub_f32_e32 v84, v84, v242
	v_sub_f32_e32 v85, v85, v242
	v_sub_f32_e32 v86, v86, v242
	v_sub_f32_e32 v87, v87, v242
	v_sub_f32_e32 v88, v88, v242
	v_sub_f32_e32 v89, v89, v242
	v_sub_f32_e32 v90, v90, v242
	v_sub_f32_e32 v91, v91, v242
	v_sub_f32_e32 v92, v92, v242
	v_sub_f32_e32 v93, v93, v242
	v_sub_f32_e32 v94, v94, v242
	v_sub_f32_e32 v95, v95, v242
	v_sub_f32_e32 v96, v96, v242
	v_sub_f32_e32 v97, v97, v242
	v_sub_f32_e32 v98, v98, v242
	v_sub_f32_e32 v99, v99, v242
	v_sub_f32_e32 v68, v68, v242
	v_sub_f32_e32 v69, v69, v242
	v_sub_f32_e32 v70, v70, v242
	v_sub_f32_e32 v71, v71, v242
	v_sub_f32_e32 v72, v72, v242
	v_sub_f32_e32 v73, v73, v242
	v_sub_f32_e32 v74, v74, v242
	v_sub_f32_e32 v75, v75, v242
	v_sub_f32_e32 v76, v76, v242
	v_sub_f32_e32 v77, v77, v242
	v_sub_f32_e32 v78, v78, v242
	v_sub_f32_e32 v79, v79, v242
	v_sub_f32_e32 v80, v80, v242
	v_sub_f32_e32 v81, v81, v242
	v_sub_f32_e32 v82, v82, v242
	v_sub_f32_e32 v83, v83, v242
	v_cmp_lt_f32_e32 vcc, 0xf0000000, v241
	v_sub_f32_e32 v242, 0, v241
	s_nop 0
	v_cndmask_b32_e32 v242, 0, v242, vcc
	v_add_f32_e32 v240, v241, v242
	v_mov_b32_e32 v184, v242
	v_mov_b32_e32 v185, v242
	v_mov_b32_e32 v186, v242
	v_mov_b32_e32 v187, v242
	v_mov_b32_e32 v188, v242
	v_mov_b32_e32 v189, v242
	v_mov_b32_e32 v190, v242
	v_mov_b32_e32 v191, v242
	v_mov_b32_e32 v192, v242
	v_mov_b32_e32 v193, v242
	v_mov_b32_e32 v194, v242
	v_mov_b32_e32 v195, v242
	v_mov_b32_e32 v196, v242
	v_mov_b32_e32 v197, v242
	v_mov_b32_e32 v198, v242
	v_mov_b32_e32 v199, v242
	s_branch .LBB0_958
	s_nop 0
	s_nop 0
	s_nop 0
	s_nop 0
	s_nop 0
	s_nop 0
	s_nop 0
	s_nop 0
	s_nop 0
	s_nop 0
	s_nop 0
	s_nop 0
	s_nop 0
	s_nop 0
